# no-zero variant plus write-through (sc1) stores everywhere and the L2 writeback removed from the grid barrier
# baseline (speedup 1.0000x reference)
.LBB0_22:
	global_load_dword v208, v[6:7], off
	v_lshl_add_u64 v[18:19], v[6:7], 0, s[20:21]
	global_load_dword v209, v[18:19], off
	v_lshl_add_u64 v[18:19], v[18:19], 0, s[20:21]
	global_load_dword v210, v[18:19], off
	v_lshl_add_u64 v[18:19], v[18:19], 0, s[20:21]
	global_load_dword v211, v[18:19], off
	v_lshl_add_u64 v[18:19], v[18:19], 0, s[20:21]
	global_load_dword v212, v[18:19], off
	v_lshl_add_u64 v[18:19], v[18:19], 0, s[20:21]
	global_load_dword v213, v[18:19], off
	v_lshl_add_u64 v[18:19], v[18:19], 0, s[20:21]
	global_load_dword v214, v[18:19], off
	v_lshl_add_u64 v[18:19], v[18:19], 0, s[20:21]
	global_load_dword v215, v[18:19], off
	v_lshl_add_u64 v[18:19], v[18:19], 0, s[20:21]
	global_load_dword v216, v[18:19], off
	v_lshl_add_u64 v[18:19], v[18:19], 0, s[20:21]
	global_load_dword v217, v[18:19], off
	v_lshl_add_u64 v[18:19], v[18:19], 0, s[20:21]
	global_load_dword v218, v[18:19], off
	v_lshl_add_u64 v[18:19], v[18:19], 0, s[20:21]
	global_load_dword v219, v[18:19], off
	v_lshl_add_u64 v[18:19], v[18:19], 0, s[20:21]
	global_load_dword v220, v[18:19], off
	v_lshl_add_u64 v[18:19], v[18:19], 0, s[20:21]
	global_load_dword v221, v[18:19], off
	v_lshl_add_u64 v[18:19], v[18:19], 0, s[20:21]
	global_load_dword v222, v[18:19], off
	v_lshl_add_u64 v[18:19], v[18:19], 0, s[20:21]
	global_load_dword v223, v[18:19], off
	v_lshl_add_u64 v[18:19], v[18:19], 0, s[20:21]
	global_load_dword v224, v[18:19], off
	v_lshl_add_u64 v[18:19], v[18:19], 0, s[20:21]
	global_load_dword v225, v[18:19], off
	v_lshl_add_u64 v[18:19], v[18:19], 0, s[20:21]
	global_load_dword v226, v[18:19], off
	v_lshl_add_u64 v[18:19], v[18:19], 0, s[20:21]
	global_load_dword v227, v[18:19], off
	v_lshl_add_u64 v[18:19], v[18:19], 0, s[20:21]
	global_load_dword v228, v[18:19], off
	v_lshl_add_u64 v[18:19], v[18:19], 0, s[20:21]
	global_load_dword v229, v[18:19], off
	v_lshl_add_u64 v[18:19], v[18:19], 0, s[20:21]
	global_load_dword v230, v[18:19], off
	v_lshl_add_u64 v[18:19], v[18:19], 0, s[20:21]
	global_load_dword v231, v[18:19], off
	v_lshl_add_u64 v[18:19], v[18:19], 0, s[20:21]
	global_load_dword v232, v[18:19], off
	v_lshl_add_u64 v[18:19], v[18:19], 0, s[20:21]
	global_load_dword v233, v[18:19], off
	v_lshl_add_u64 v[18:19], v[18:19], 0, s[20:21]
	global_load_dword v234, v[18:19], off
	v_lshl_add_u64 v[18:19], v[18:19], 0, s[20:21]
	global_load_dword v235, v[18:19], off
	v_lshl_add_u64 v[18:19], v[18:19], 0, s[20:21]
	global_load_dword v236, v[18:19], off
	v_lshl_add_u64 v[18:19], v[18:19], 0, s[20:21]
	global_load_dword v237, v[18:19], off
	v_lshl_add_u64 v[18:19], v[18:19], 0, s[20:21]
	global_load_dword v238, v[18:19], off
	v_lshl_add_u64 v[18:19], v[18:19], 0, s[20:21]
	global_load_dword v239, v[18:19], off
	v_lshl_add_u64 v[18:19], v[18:19], 0, s[20:21]
	global_load_dword v240, v[18:19], off
	v_lshl_add_u64 v[18:19], v[18:19], 0, s[20:21]
	global_load_dword v241, v[18:19], off
	v_lshl_add_u64 v[18:19], v[18:19], 0, s[20:21]
	global_load_dword v242, v[18:19], off
	v_lshl_add_u64 v[18:19], v[18:19], 0, s[20:21]
	global_load_dword v243, v[18:19], off
	v_lshl_add_u64 v[18:19], v[18:19], 0, s[20:21]
	global_load_dword v244, v[18:19], off
	v_lshl_add_u64 v[18:19], v[18:19], 0, s[20:21]
	global_load_dword v245, v[18:19], off
	v_lshl_add_u64 v[18:19], v[18:19], 0, s[20:21]
	global_load_dword v182, v[18:19], off
	v_lshl_add_u64 v[18:19], v[18:19], 0, s[20:21]
	global_load_dword v183, v[18:19], off
	v_lshl_add_u64 v[18:19], v[18:19], 0, s[20:21]
	global_load_dword v184, v[18:19], off
	v_lshl_add_u64 v[18:19], v[18:19], 0, s[20:21]
	global_load_dword v185, v[18:19], off
	v_lshl_add_u64 v[18:19], v[18:19], 0, s[20:21]
	global_load_dword v186, v[18:19], off
	v_lshl_add_u64 v[18:19], v[18:19], 0, s[20:21]
	global_load_dword v187, v[18:19], off
	v_lshl_add_u64 v[18:19], v[18:19], 0, s[20:21]
	global_load_dword v188, v[18:19], off
	v_lshl_add_u64 v[18:19], v[18:19], 0, s[20:21]
	global_load_dword v189, v[18:19], off
	v_lshl_add_u64 v[18:19], v[18:19], 0, s[20:21]
	global_load_dword v190, v[18:19], off
	v_lshl_add_u64 v[18:19], v[18:19], 0, s[20:21]
	global_load_dword v191, v[18:19], off
	v_lshl_add_u64 v[18:19], v[18:19], 0, s[20:21]
	global_load_dword v192, v[18:19], off
	v_lshl_add_u64 v[18:19], v[18:19], 0, s[20:21]
	global_load_dword v193, v[18:19], off
	v_lshl_add_u64 v[18:19], v[18:19], 0, s[20:21]
	global_load_dword v194, v[18:19], off
	v_lshl_add_u64 v[18:19], v[18:19], 0, s[20:21]
	global_load_dword v195, v[18:19], off
	v_lshl_add_u64 v[18:19], v[18:19], 0, s[20:21]
	global_load_dword v196, v[18:19], off
	v_lshl_add_u64 v[18:19], v[18:19], 0, s[20:21]
	global_load_dword v197, v[18:19], off
	v_lshl_add_u64 v[18:19], v[18:19], 0, s[20:21]
	global_load_dword v198, v[18:19], off
	v_lshl_add_u64 v[18:19], v[18:19], 0, s[20:21]
	global_load_dword v199, v[18:19], off
	v_lshl_add_u64 v[18:19], v[18:19], 0, s[20:21]
	global_load_dword v200, v[18:19], off
	v_lshl_add_u64 v[18:19], v[18:19], 0, s[20:21]
	global_load_dword v201, v[18:19], off
	v_lshl_add_u64 v[18:19], v[18:19], 0, s[20:21]
	global_load_dword v202, v[18:19], off
	v_lshl_add_u64 v[18:19], v[18:19], 0, s[20:21]
	global_load_dword v203, v[18:19], off
	v_lshl_add_u64 v[18:19], v[18:19], 0, s[20:21]
	global_load_dword v22, v[18:19], off
	v_lshl_add_u64 v[18:19], v[18:19], 0, s[20:21]
	global_load_dword v23, v[18:19], off
	v_lshl_add_u64 v[18:19], v[18:19], 0, s[20:21]
	global_load_dword v24, v[18:19], off
	v_lshl_add_u64 v[18:19], v[18:19], 0, s[20:21]
	global_load_dword v25, v[18:19], off
	s_add_i32 s23, s44, s22
	v_mov_b32_e32 v21, s23
	v_lshl_add_u64 v[6:7], v[6:7], 0, s[12:13]
	v_lshl_add_u64 v[6:7], v[6:7], 0, s[12:13]
	s_addk_i32 s22, 0x800
	ds_read_b128 v[146:149], v21 offset:0
	ds_read_b128 v[150:153], v21 offset:16
	ds_read_b128 v[154:157], v21 offset:32
	ds_read_b128 v[158:161], v21 offset:48
	ds_read_b128 v[162:165], v21 offset:64
	ds_read_b128 v[166:169], v21 offset:80
	ds_read_b128 v[26:29], v21 offset:96
	ds_read_b128 v[30:33], v21 offset:112
	s_waitcnt vmcnt(63) lgkmcnt(6)
	v_pk_fma_f32 v[10:11], v[208:209], v[146:147], v[10:11] op_sel_hi:[0,1,1]
	v_pk_fma_f32 v[14:15], v[208:209], v[148:149], v[14:15] op_sel_hi:[0,1,1]
	v_pk_fma_f32 v[12:13], v[208:209], v[150:151], v[12:13] op_sel_hi:[0,1,1]
	v_pk_fma_f32 v[8:9], v[208:209], v[152:153], v[8:9] op_sel_hi:[0,1,1]
	ds_read_b128 v[146:149], v21 offset:128
	ds_read_b128 v[150:153], v21 offset:144
	s_waitcnt vmcnt(62) lgkmcnt(6)
	v_pk_fma_f32 v[10:11], v[208:209], v[154:155], v[10:11] op_sel:[1,0,0] op_sel_hi:[1,1,1]
	v_pk_fma_f32 v[14:15], v[208:209], v[156:157], v[14:15] op_sel:[1,0,0] op_sel_hi:[1,1,1]
	v_pk_fma_f32 v[12:13], v[208:209], v[158:159], v[12:13] op_sel:[1,0,0] op_sel_hi:[1,1,1]
	v_pk_fma_f32 v[8:9], v[208:209], v[160:161], v[8:9] op_sel:[1,0,0] op_sel_hi:[1,1,1]
	ds_read_b128 v[154:157], v21 offset:160
	ds_read_b128 v[158:161], v21 offset:176
	s_waitcnt vmcnt(61) lgkmcnt(6)
	v_pk_fma_f32 v[10:11], v[210:211], v[162:163], v[10:11] op_sel_hi:[0,1,1]
	v_pk_fma_f32 v[14:15], v[210:211], v[164:165], v[14:15] op_sel_hi:[0,1,1]
	v_pk_fma_f32 v[12:13], v[210:211], v[166:167], v[12:13] op_sel_hi:[0,1,1]
	v_pk_fma_f32 v[8:9], v[210:211], v[168:169], v[8:9] op_sel_hi:[0,1,1]
	ds_read_b128 v[162:165], v21 offset:192
	ds_read_b128 v[166:169], v21 offset:208
	s_waitcnt vmcnt(60) lgkmcnt(6)
	v_pk_fma_f32 v[10:11], v[210:211], v[26:27], v[10:11] op_sel:[1,0,0] op_sel_hi:[1,1,1]
	v_pk_fma_f32 v[14:15], v[210:211], v[28:29], v[14:15] op_sel:[1,0,0] op_sel_hi:[1,1,1]
	v_pk_fma_f32 v[12:13], v[210:211], v[30:31], v[12:13] op_sel:[1,0,0] op_sel_hi:[1,1,1]
	v_pk_fma_f32 v[8:9], v[210:211], v[32:33], v[8:9] op_sel:[1,0,0] op_sel_hi:[1,1,1]
	ds_read_b128 v[26:29], v21 offset:224
	ds_read_b128 v[30:33], v21 offset:240
	s_waitcnt vmcnt(59) lgkmcnt(6)
	v_pk_fma_f32 v[10:11], v[212:213], v[146:147], v[10:11] op_sel_hi:[0,1,1]
	v_pk_fma_f32 v[14:15], v[212:213], v[148:149], v[14:15] op_sel_hi:[0,1,1]
	v_pk_fma_f32 v[12:13], v[212:213], v[150:151], v[12:13] op_sel_hi:[0,1,1]
	v_pk_fma_f32 v[8:9], v[212:213], v[152:153], v[8:9] op_sel_hi:[0,1,1]
	ds_read_b128 v[146:149], v21 offset:256
	ds_read_b128 v[150:153], v21 offset:272
	s_waitcnt vmcnt(58) lgkmcnt(6)
	v_pk_fma_f32 v[10:11], v[212:213], v[154:155], v[10:11] op_sel:[1,0,0] op_sel_hi:[1,1,1]
	v_pk_fma_f32 v[14:15], v[212:213], v[156:157], v[14:15] op_sel:[1,0,0] op_sel_hi:[1,1,1]
	v_pk_fma_f32 v[12:13], v[212:213], v[158:159], v[12:13] op_sel:[1,0,0] op_sel_hi:[1,1,1]
	v_pk_fma_f32 v[8:9], v[212:213], v[160:161], v[8:9] op_sel:[1,0,0] op_sel_hi:[1,1,1]
	ds_read_b128 v[154:157], v21 offset:288
	ds_read_b128 v[158:161], v21 offset:304
	s_waitcnt vmcnt(57) lgkmcnt(6)
	v_pk_fma_f32 v[10:11], v[214:215], v[162:163], v[10:11] op_sel_hi:[0,1,1]
	v_pk_fma_f32 v[14:15], v[214:215], v[164:165], v[14:15] op_sel_hi:[0,1,1]
	v_pk_fma_f32 v[12:13], v[214:215], v[166:167], v[12:13] op_sel_hi:[0,1,1]
	v_pk_fma_f32 v[8:9], v[214:215], v[168:169], v[8:9] op_sel_hi:[0,1,1]
	ds_read_b128 v[162:165], v21 offset:320
	ds_read_b128 v[166:169], v21 offset:336
	s_waitcnt vmcnt(56) lgkmcnt(6)
	v_pk_fma_f32 v[10:11], v[214:215], v[26:27], v[10:11] op_sel:[1,0,0] op_sel_hi:[1,1,1]
	v_pk_fma_f32 v[14:15], v[214:215], v[28:29], v[14:15] op_sel:[1,0,0] op_sel_hi:[1,1,1]
	v_pk_fma_f32 v[12:13], v[214:215], v[30:31], v[12:13] op_sel:[1,0,0] op_sel_hi:[1,1,1]
	v_pk_fma_f32 v[8:9], v[214:215], v[32:33], v[8:9] op_sel:[1,0,0] op_sel_hi:[1,1,1]
	ds_read_b128 v[26:29], v21 offset:352
	ds_read_b128 v[30:33], v21 offset:368
	s_waitcnt vmcnt(55) lgkmcnt(6)
	v_pk_fma_f32 v[10:11], v[216:217], v[146:147], v[10:11] op_sel_hi:[0,1,1]
	v_pk_fma_f32 v[14:15], v[216:217], v[148:149], v[14:15] op_sel_hi:[0,1,1]
	v_pk_fma_f32 v[12:13], v[216:217], v[150:151], v[12:13] op_sel_hi:[0,1,1]
	v_pk_fma_f32 v[8:9], v[216:217], v[152:153], v[8:9] op_sel_hi:[0,1,1]
	ds_read_b128 v[146:149], v21 offset:384
	ds_read_b128 v[150:153], v21 offset:400
	s_waitcnt vmcnt(54) lgkmcnt(6)
	v_pk_fma_f32 v[10:11], v[216:217], v[154:155], v[10:11] op_sel:[1,0,0] op_sel_hi:[1,1,1]
	v_pk_fma_f32 v[14:15], v[216:217], v[156:157], v[14:15] op_sel:[1,0,0] op_sel_hi:[1,1,1]
	v_pk_fma_f32 v[12:13], v[216:217], v[158:159], v[12:13] op_sel:[1,0,0] op_sel_hi:[1,1,1]
	v_pk_fma_f32 v[8:9], v[216:217], v[160:161], v[8:9] op_sel:[1,0,0] op_sel_hi:[1,1,1]
	ds_read_b128 v[154:157], v21 offset:416
	ds_read_b128 v[158:161], v21 offset:432
	s_waitcnt vmcnt(53) lgkmcnt(6)
	v_pk_fma_f32 v[10:11], v[218:219], v[162:163], v[10:11] op_sel_hi:[0,1,1]
	v_pk_fma_f32 v[14:15], v[218:219], v[164:165], v[14:15] op_sel_hi:[0,1,1]
	v_pk_fma_f32 v[12:13], v[218:219], v[166:167], v[12:13] op_sel_hi:[0,1,1]
	v_pk_fma_f32 v[8:9], v[218:219], v[168:169], v[8:9] op_sel_hi:[0,1,1]
	ds_read_b128 v[162:165], v21 offset:448
	ds_read_b128 v[166:169], v21 offset:464
	s_waitcnt vmcnt(52) lgkmcnt(6)
	v_pk_fma_f32 v[10:11], v[218:219], v[26:27], v[10:11] op_sel:[1,0,0] op_sel_hi:[1,1,1]
	v_pk_fma_f32 v[14:15], v[218:219], v[28:29], v[14:15] op_sel:[1,0,0] op_sel_hi:[1,1,1]
	v_pk_fma_f32 v[12:13], v[218:219], v[30:31], v[12:13] op_sel:[1,0,0] op_sel_hi:[1,1,1]
	v_pk_fma_f32 v[8:9], v[218:219], v[32:33], v[8:9] op_sel:[1,0,0] op_sel_hi:[1,1,1]
	ds_read_b128 v[26:29], v21 offset:480
	ds_read_b128 v[30:33], v21 offset:496
	s_waitcnt vmcnt(51) lgkmcnt(6)
	v_pk_fma_f32 v[10:11], v[220:221], v[146:147], v[10:11] op_sel_hi:[0,1,1]
	v_pk_fma_f32 v[14:15], v[220:221], v[148:149], v[14:15] op_sel_hi:[0,1,1]
	v_pk_fma_f32 v[12:13], v[220:221], v[150:151], v[12:13] op_sel_hi:[0,1,1]
	v_pk_fma_f32 v[8:9], v[220:221], v[152:153], v[8:9] op_sel_hi:[0,1,1]
	ds_read_b128 v[146:149], v21 offset:512
	ds_read_b128 v[150:153], v21 offset:528
	s_waitcnt vmcnt(50) lgkmcnt(6)
	v_pk_fma_f32 v[10:11], v[220:221], v[154:155], v[10:11] op_sel:[1,0,0] op_sel_hi:[1,1,1]
	v_pk_fma_f32 v[14:15], v[220:221], v[156:157], v[14:15] op_sel:[1,0,0] op_sel_hi:[1,1,1]
	v_pk_fma_f32 v[12:13], v[220:221], v[158:159], v[12:13] op_sel:[1,0,0] op_sel_hi:[1,1,1]
	v_pk_fma_f32 v[8:9], v[220:221], v[160:161], v[8:9] op_sel:[1,0,0] op_sel_hi:[1,1,1]
	ds_read_b128 v[154:157], v21 offset:544
	ds_read_b128 v[158:161], v21 offset:560
	s_waitcnt vmcnt(49) lgkmcnt(6)
	v_pk_fma_f32 v[10:11], v[222:223], v[162:163], v[10:11] op_sel_hi:[0,1,1]
	v_pk_fma_f32 v[14:15], v[222:223], v[164:165], v[14:15] op_sel_hi:[0,1,1]
	v_pk_fma_f32 v[12:13], v[222:223], v[166:167], v[12:13] op_sel_hi:[0,1,1]
	v_pk_fma_f32 v[8:9], v[222:223], v[168:169], v[8:9] op_sel_hi:[0,1,1]
	ds_read_b128 v[162:165], v21 offset:576
	ds_read_b128 v[166:169], v21 offset:592
	s_waitcnt vmcnt(48) lgkmcnt(6)
	v_pk_fma_f32 v[10:11], v[222:223], v[26:27], v[10:11] op_sel:[1,0,0] op_sel_hi:[1,1,1]
	v_pk_fma_f32 v[14:15], v[222:223], v[28:29], v[14:15] op_sel:[1,0,0] op_sel_hi:[1,1,1]
	v_pk_fma_f32 v[12:13], v[222:223], v[30:31], v[12:13] op_sel:[1,0,0] op_sel_hi:[1,1,1]
	v_pk_fma_f32 v[8:9], v[222:223], v[32:33], v[8:9] op_sel:[1,0,0] op_sel_hi:[1,1,1]
	ds_read_b128 v[26:29], v21 offset:608
	ds_read_b128 v[30:33], v21 offset:624
	s_waitcnt vmcnt(47) lgkmcnt(6)
	v_pk_fma_f32 v[10:11], v[224:225], v[146:147], v[10:11] op_sel_hi:[0,1,1]
	v_pk_fma_f32 v[14:15], v[224:225], v[148:149], v[14:15] op_sel_hi:[0,1,1]
	v_pk_fma_f32 v[12:13], v[224:225], v[150:151], v[12:13] op_sel_hi:[0,1,1]
	v_pk_fma_f32 v[8:9], v[224:225], v[152:153], v[8:9] op_sel_hi:[0,1,1]
	ds_read_b128 v[146:149], v21 offset:640
	ds_read_b128 v[150:153], v21 offset:656
	s_waitcnt vmcnt(46) lgkmcnt(6)
	v_pk_fma_f32 v[10:11], v[224:225], v[154:155], v[10:11] op_sel:[1,0,0] op_sel_hi:[1,1,1]
	v_pk_fma_f32 v[14:15], v[224:225], v[156:157], v[14:15] op_sel:[1,0,0] op_sel_hi:[1,1,1]
	v_pk_fma_f32 v[12:13], v[224:225], v[158:159], v[12:13] op_sel:[1,0,0] op_sel_hi:[1,1,1]
	v_pk_fma_f32 v[8:9], v[224:225], v[160:161], v[8:9] op_sel:[1,0,0] op_sel_hi:[1,1,1]
	ds_read_b128 v[154:157], v21 offset:672
	ds_read_b128 v[158:161], v21 offset:688
	s_waitcnt vmcnt(45) lgkmcnt(6)
	v_pk_fma_f32 v[10:11], v[226:227], v[162:163], v[10:11] op_sel_hi:[0,1,1]
	v_pk_fma_f32 v[14:15], v[226:227], v[164:165], v[14:15] op_sel_hi:[0,1,1]
	v_pk_fma_f32 v[12:13], v[226:227], v[166:167], v[12:13] op_sel_hi:[0,1,1]
	v_pk_fma_f32 v[8:9], v[226:227], v[168:169], v[8:9] op_sel_hi:[0,1,1]
	ds_read_b128 v[162:165], v21 offset:704
	ds_read_b128 v[166:169], v21 offset:720
	s_waitcnt vmcnt(44) lgkmcnt(6)
	v_pk_fma_f32 v[10:11], v[226:227], v[26:27], v[10:11] op_sel:[1,0,0] op_sel_hi:[1,1,1]
	v_pk_fma_f32 v[14:15], v[226:227], v[28:29], v[14:15] op_sel:[1,0,0] op_sel_hi:[1,1,1]
	v_pk_fma_f32 v[12:13], v[226:227], v[30:31], v[12:13] op_sel:[1,0,0] op_sel_hi:[1,1,1]
	v_pk_fma_f32 v[8:9], v[226:227], v[32:33], v[8:9] op_sel:[1,0,0] op_sel_hi:[1,1,1]
	ds_read_b128 v[26:29], v21 offset:736
	ds_read_b128 v[30:33], v21 offset:752
	s_waitcnt vmcnt(43) lgkmcnt(6)
	v_pk_fma_f32 v[10:11], v[228:229], v[146:147], v[10:11] op_sel_hi:[0,1,1]
	v_pk_fma_f32 v[14:15], v[228:229], v[148:149], v[14:15] op_sel_hi:[0,1,1]
	v_pk_fma_f32 v[12:13], v[228:229], v[150:151], v[12:13] op_sel_hi:[0,1,1]
	v_pk_fma_f32 v[8:9], v[228:229], v[152:153], v[8:9] op_sel_hi:[0,1,1]
	ds_read_b128 v[146:149], v21 offset:768
	ds_read_b128 v[150:153], v21 offset:784
	s_waitcnt vmcnt(42) lgkmcnt(6)
	v_pk_fma_f32 v[10:11], v[228:229], v[154:155], v[10:11] op_sel:[1,0,0] op_sel_hi:[1,1,1]
	v_pk_fma_f32 v[14:15], v[228:229], v[156:157], v[14:15] op_sel:[1,0,0] op_sel_hi:[1,1,1]
	v_pk_fma_f32 v[12:13], v[228:229], v[158:159], v[12:13] op_sel:[1,0,0] op_sel_hi:[1,1,1]
	v_pk_fma_f32 v[8:9], v[228:229], v[160:161], v[8:9] op_sel:[1,0,0] op_sel_hi:[1,1,1]
	ds_read_b128 v[154:157], v21 offset:800
	ds_read_b128 v[158:161], v21 offset:816
	s_waitcnt vmcnt(41) lgkmcnt(6)
	v_pk_fma_f32 v[10:11], v[230:231], v[162:163], v[10:11] op_sel_hi:[0,1,1]
	v_pk_fma_f32 v[14:15], v[230:231], v[164:165], v[14:15] op_sel_hi:[0,1,1]
	v_pk_fma_f32 v[12:13], v[230:231], v[166:167], v[12:13] op_sel_hi:[0,1,1]
	v_pk_fma_f32 v[8:9], v[230:231], v[168:169], v[8:9] op_sel_hi:[0,1,1]
	ds_read_b128 v[162:165], v21 offset:832
	ds_read_b128 v[166:169], v21 offset:848
	s_waitcnt vmcnt(40) lgkmcnt(6)
	v_pk_fma_f32 v[10:11], v[230:231], v[26:27], v[10:11] op_sel:[1,0,0] op_sel_hi:[1,1,1]
	v_pk_fma_f32 v[14:15], v[230:231], v[28:29], v[14:15] op_sel:[1,0,0] op_sel_hi:[1,1,1]
	v_pk_fma_f32 v[12:13], v[230:231], v[30:31], v[12:13] op_sel:[1,0,0] op_sel_hi:[1,1,1]
	v_pk_fma_f32 v[8:9], v[230:231], v[32:33], v[8:9] op_sel:[1,0,0] op_sel_hi:[1,1,1]
	ds_read_b128 v[26:29], v21 offset:864
	ds_read_b128 v[30:33], v21 offset:880
	s_waitcnt vmcnt(39) lgkmcnt(6)
	v_pk_fma_f32 v[10:11], v[232:233], v[146:147], v[10:11] op_sel_hi:[0,1,1]
	v_pk_fma_f32 v[14:15], v[232:233], v[148:149], v[14:15] op_sel_hi:[0,1,1]
	v_pk_fma_f32 v[12:13], v[232:233], v[150:151], v[12:13] op_sel_hi:[0,1,1]
	v_pk_fma_f32 v[8:9], v[232:233], v[152:153], v[8:9] op_sel_hi:[0,1,1]
	ds_read_b128 v[146:149], v21 offset:896
	ds_read_b128 v[150:153], v21 offset:912
	s_waitcnt vmcnt(38) lgkmcnt(6)
	v_pk_fma_f32 v[10:11], v[232:233], v[154:155], v[10:11] op_sel:[1,0,0] op_sel_hi:[1,1,1]
	v_pk_fma_f32 v[14:15], v[232:233], v[156:157], v[14:15] op_sel:[1,0,0] op_sel_hi:[1,1,1]
	v_pk_fma_f32 v[12:13], v[232:233], v[158:159], v[12:13] op_sel:[1,0,0] op_sel_hi:[1,1,1]
	v_pk_fma_f32 v[8:9], v[232:233], v[160:161], v[8:9] op_sel:[1,0,0] op_sel_hi:[1,1,1]
	ds_read_b128 v[154:157], v21 offset:928
	ds_read_b128 v[158:161], v21 offset:944
	s_waitcnt vmcnt(37) lgkmcnt(6)
	v_pk_fma_f32 v[10:11], v[234:235], v[162:163], v[10:11] op_sel_hi:[0,1,1]
	v_pk_fma_f32 v[14:15], v[234:235], v[164:165], v[14:15] op_sel_hi:[0,1,1]
	v_pk_fma_f32 v[12:13], v[234:235], v[166:167], v[12:13] op_sel_hi:[0,1,1]
	v_pk_fma_f32 v[8:9], v[234:235], v[168:169], v[8:9] op_sel_hi:[0,1,1]
	ds_read_b128 v[162:165], v21 offset:960
	ds_read_b128 v[166:169], v21 offset:976
	s_waitcnt vmcnt(36) lgkmcnt(6)
	v_pk_fma_f32 v[10:11], v[234:235], v[26:27], v[10:11] op_sel:[1,0,0] op_sel_hi:[1,1,1]
	v_pk_fma_f32 v[14:15], v[234:235], v[28:29], v[14:15] op_sel:[1,0,0] op_sel_hi:[1,1,1]
	v_pk_fma_f32 v[12:13], v[234:235], v[30:31], v[12:13] op_sel:[1,0,0] op_sel_hi:[1,1,1]
	v_pk_fma_f32 v[8:9], v[234:235], v[32:33], v[8:9] op_sel:[1,0,0] op_sel_hi:[1,1,1]
	ds_read_b128 v[26:29], v21 offset:992
	ds_read_b128 v[30:33], v21 offset:1008
	s_waitcnt vmcnt(35) lgkmcnt(6)
	v_pk_fma_f32 v[10:11], v[236:237], v[146:147], v[10:11] op_sel_hi:[0,1,1]
	v_pk_fma_f32 v[14:15], v[236:237], v[148:149], v[14:15] op_sel_hi:[0,1,1]
	v_pk_fma_f32 v[12:13], v[236:237], v[150:151], v[12:13] op_sel_hi:[0,1,1]
	v_pk_fma_f32 v[8:9], v[236:237], v[152:153], v[8:9] op_sel_hi:[0,1,1]
	ds_read_b128 v[146:149], v21 offset:1024
	ds_read_b128 v[150:153], v21 offset:1040
	s_waitcnt vmcnt(34) lgkmcnt(6)
	v_pk_fma_f32 v[10:11], v[236:237], v[154:155], v[10:11] op_sel:[1,0,0] op_sel_hi:[1,1,1]
	v_pk_fma_f32 v[14:15], v[236:237], v[156:157], v[14:15] op_sel:[1,0,0] op_sel_hi:[1,1,1]
	v_pk_fma_f32 v[12:13], v[236:237], v[158:159], v[12:13] op_sel:[1,0,0] op_sel_hi:[1,1,1]
	v_pk_fma_f32 v[8:9], v[236:237], v[160:161], v[8:9] op_sel:[1,0,0] op_sel_hi:[1,1,1]
	ds_read_b128 v[154:157], v21 offset:1056
	ds_read_b128 v[158:161], v21 offset:1072
	s_waitcnt vmcnt(33) lgkmcnt(6)
	v_pk_fma_f32 v[10:11], v[238:239], v[162:163], v[10:11] op_sel_hi:[0,1,1]
	v_pk_fma_f32 v[14:15], v[238:239], v[164:165], v[14:15] op_sel_hi:[0,1,1]
	v_pk_fma_f32 v[12:13], v[238:239], v[166:167], v[12:13] op_sel_hi:[0,1,1]
	v_pk_fma_f32 v[8:9], v[238:239], v[168:169], v[8:9] op_sel_hi:[0,1,1]
	ds_read_b128 v[162:165], v21 offset:1088
	ds_read_b128 v[166:169], v21 offset:1104
	s_waitcnt vmcnt(32) lgkmcnt(6)
	v_pk_fma_f32 v[10:11], v[238:239], v[26:27], v[10:11] op_sel:[1,0,0] op_sel_hi:[1,1,1]
	v_pk_fma_f32 v[14:15], v[238:239], v[28:29], v[14:15] op_sel:[1,0,0] op_sel_hi:[1,1,1]
	v_pk_fma_f32 v[12:13], v[238:239], v[30:31], v[12:13] op_sel:[1,0,0] op_sel_hi:[1,1,1]
	v_pk_fma_f32 v[8:9], v[238:239], v[32:33], v[8:9] op_sel:[1,0,0] op_sel_hi:[1,1,1]
	ds_read_b128 v[26:29], v21 offset:1120
	ds_read_b128 v[30:33], v21 offset:1136
	s_waitcnt vmcnt(31) lgkmcnt(6)
	v_pk_fma_f32 v[10:11], v[240:241], v[146:147], v[10:11] op_sel_hi:[0,1,1]
	v_pk_fma_f32 v[14:15], v[240:241], v[148:149], v[14:15] op_sel_hi:[0,1,1]
	v_pk_fma_f32 v[12:13], v[240:241], v[150:151], v[12:13] op_sel_hi:[0,1,1]
	v_pk_fma_f32 v[8:9], v[240:241], v[152:153], v[8:9] op_sel_hi:[0,1,1]
	ds_read_b128 v[146:149], v21 offset:1152
	ds_read_b128 v[150:153], v21 offset:1168
	s_waitcnt vmcnt(30) lgkmcnt(6)
	v_pk_fma_f32 v[10:11], v[240:241], v[154:155], v[10:11] op_sel:[1,0,0] op_sel_hi:[1,1,1]
	v_pk_fma_f32 v[14:15], v[240:241], v[156:157], v[14:15] op_sel:[1,0,0] op_sel_hi:[1,1,1]
	v_pk_fma_f32 v[12:13], v[240:241], v[158:159], v[12:13] op_sel:[1,0,0] op_sel_hi:[1,1,1]
	v_pk_fma_f32 v[8:9], v[240:241], v[160:161], v[8:9] op_sel:[1,0,0] op_sel_hi:[1,1,1]
	ds_read_b128 v[154:157], v21 offset:1184
	ds_read_b128 v[158:161], v21 offset:1200
	s_waitcnt vmcnt(29) lgkmcnt(6)
	v_pk_fma_f32 v[10:11], v[242:243], v[162:163], v[10:11] op_sel_hi:[0,1,1]
	v_pk_fma_f32 v[14:15], v[242:243], v[164:165], v[14:15] op_sel_hi:[0,1,1]
	v_pk_fma_f32 v[12:13], v[242:243], v[166:167], v[12:13] op_sel_hi:[0,1,1]
	v_pk_fma_f32 v[8:9], v[242:243], v[168:169], v[8:9] op_sel_hi:[0,1,1]
	ds_read_b128 v[162:165], v21 offset:1216
	ds_read_b128 v[166:169], v21 offset:1232
	s_waitcnt vmcnt(28) lgkmcnt(6)
	v_pk_fma_f32 v[10:11], v[242:243], v[26:27], v[10:11] op_sel:[1,0,0] op_sel_hi:[1,1,1]
	v_pk_fma_f32 v[14:15], v[242:243], v[28:29], v[14:15] op_sel:[1,0,0] op_sel_hi:[1,1,1]
	v_pk_fma_f32 v[12:13], v[242:243], v[30:31], v[12:13] op_sel:[1,0,0] op_sel_hi:[1,1,1]
	v_pk_fma_f32 v[8:9], v[242:243], v[32:33], v[8:9] op_sel:[1,0,0] op_sel_hi:[1,1,1]
	ds_read_b128 v[26:29], v21 offset:1248
	ds_read_b128 v[30:33], v21 offset:1264
	s_waitcnt vmcnt(27) lgkmcnt(6)
	v_pk_fma_f32 v[10:11], v[244:245], v[146:147], v[10:11] op_sel_hi:[0,1,1]
	v_pk_fma_f32 v[14:15], v[244:245], v[148:149], v[14:15] op_sel_hi:[0,1,1]
	v_pk_fma_f32 v[12:13], v[244:245], v[150:151], v[12:13] op_sel_hi:[0,1,1]
	v_pk_fma_f32 v[8:9], v[244:245], v[152:153], v[8:9] op_sel_hi:[0,1,1]
	ds_read_b128 v[146:149], v21 offset:1280
	ds_read_b128 v[150:153], v21 offset:1296
	s_waitcnt vmcnt(26) lgkmcnt(6)
	v_pk_fma_f32 v[10:11], v[244:245], v[154:155], v[10:11] op_sel:[1,0,0] op_sel_hi:[1,1,1]
	v_pk_fma_f32 v[14:15], v[244:245], v[156:157], v[14:15] op_sel:[1,0,0] op_sel_hi:[1,1,1]
	v_pk_fma_f32 v[12:13], v[244:245], v[158:159], v[12:13] op_sel:[1,0,0] op_sel_hi:[1,1,1]
	v_pk_fma_f32 v[8:9], v[244:245], v[160:161], v[8:9] op_sel:[1,0,0] op_sel_hi:[1,1,1]
	ds_read_b128 v[154:157], v21 offset:1312
	ds_read_b128 v[158:161], v21 offset:1328
	s_waitcnt vmcnt(25) lgkmcnt(6)
	v_pk_fma_f32 v[10:11], v[182:183], v[162:163], v[10:11] op_sel_hi:[0,1,1]
	v_pk_fma_f32 v[14:15], v[182:183], v[164:165], v[14:15] op_sel_hi:[0,1,1]
	v_pk_fma_f32 v[12:13], v[182:183], v[166:167], v[12:13] op_sel_hi:[0,1,1]
	v_pk_fma_f32 v[8:9], v[182:183], v[168:169], v[8:9] op_sel_hi:[0,1,1]
	ds_read_b128 v[162:165], v21 offset:1344
	ds_read_b128 v[166:169], v21 offset:1360
	s_waitcnt vmcnt(24) lgkmcnt(6)
	v_pk_fma_f32 v[10:11], v[182:183], v[26:27], v[10:11] op_sel:[1,0,0] op_sel_hi:[1,1,1]
	v_pk_fma_f32 v[14:15], v[182:183], v[28:29], v[14:15] op_sel:[1,0,0] op_sel_hi:[1,1,1]
	v_pk_fma_f32 v[12:13], v[182:183], v[30:31], v[12:13] op_sel:[1,0,0] op_sel_hi:[1,1,1]
	v_pk_fma_f32 v[8:9], v[182:183], v[32:33], v[8:9] op_sel:[1,0,0] op_sel_hi:[1,1,1]
	ds_read_b128 v[26:29], v21 offset:1376
	ds_read_b128 v[30:33], v21 offset:1392
	s_waitcnt vmcnt(23) lgkmcnt(6)
	v_pk_fma_f32 v[10:11], v[184:185], v[146:147], v[10:11] op_sel_hi:[0,1,1]
	v_pk_fma_f32 v[14:15], v[184:185], v[148:149], v[14:15] op_sel_hi:[0,1,1]
	v_pk_fma_f32 v[12:13], v[184:185], v[150:151], v[12:13] op_sel_hi:[0,1,1]
	v_pk_fma_f32 v[8:9], v[184:185], v[152:153], v[8:9] op_sel_hi:[0,1,1]
	ds_read_b128 v[146:149], v21 offset:1408
	ds_read_b128 v[150:153], v21 offset:1424
	s_waitcnt vmcnt(22) lgkmcnt(6)
	v_pk_fma_f32 v[10:11], v[184:185], v[154:155], v[10:11] op_sel:[1,0,0] op_sel_hi:[1,1,1]
	v_pk_fma_f32 v[14:15], v[184:185], v[156:157], v[14:15] op_sel:[1,0,0] op_sel_hi:[1,1,1]
	v_pk_fma_f32 v[12:13], v[184:185], v[158:159], v[12:13] op_sel:[1,0,0] op_sel_hi:[1,1,1]
	v_pk_fma_f32 v[8:9], v[184:185], v[160:161], v[8:9] op_sel:[1,0,0] op_sel_hi:[1,1,1]
	ds_read_b128 v[154:157], v21 offset:1440
	ds_read_b128 v[158:161], v21 offset:1456
	s_waitcnt vmcnt(21) lgkmcnt(6)
	v_pk_fma_f32 v[10:11], v[186:187], v[162:163], v[10:11] op_sel_hi:[0,1,1]
	v_pk_fma_f32 v[14:15], v[186:187], v[164:165], v[14:15] op_sel_hi:[0,1,1]
	v_pk_fma_f32 v[12:13], v[186:187], v[166:167], v[12:13] op_sel_hi:[0,1,1]
	v_pk_fma_f32 v[8:9], v[186:187], v[168:169], v[8:9] op_sel_hi:[0,1,1]
	ds_read_b128 v[162:165], v21 offset:1472
	ds_read_b128 v[166:169], v21 offset:1488
	s_waitcnt vmcnt(20) lgkmcnt(6)
	v_pk_fma_f32 v[10:11], v[186:187], v[26:27], v[10:11] op_sel:[1,0,0] op_sel_hi:[1,1,1]
	v_pk_fma_f32 v[14:15], v[186:187], v[28:29], v[14:15] op_sel:[1,0,0] op_sel_hi:[1,1,1]
	v_pk_fma_f32 v[12:13], v[186:187], v[30:31], v[12:13] op_sel:[1,0,0] op_sel_hi:[1,1,1]
	v_pk_fma_f32 v[8:9], v[186:187], v[32:33], v[8:9] op_sel:[1,0,0] op_sel_hi:[1,1,1]
	ds_read_b128 v[26:29], v21 offset:1504
	ds_read_b128 v[30:33], v21 offset:1520
	s_waitcnt vmcnt(19) lgkmcnt(6)
	v_pk_fma_f32 v[10:11], v[188:189], v[146:147], v[10:11] op_sel_hi:[0,1,1]
	v_pk_fma_f32 v[14:15], v[188:189], v[148:149], v[14:15] op_sel_hi:[0,1,1]
	v_pk_fma_f32 v[12:13], v[188:189], v[150:151], v[12:13] op_sel_hi:[0,1,1]
	v_pk_fma_f32 v[8:9], v[188:189], v[152:153], v[8:9] op_sel_hi:[0,1,1]
	ds_read_b128 v[146:149], v21 offset:1536
	ds_read_b128 v[150:153], v21 offset:1552
	s_waitcnt vmcnt(18) lgkmcnt(6)
	v_pk_fma_f32 v[10:11], v[188:189], v[154:155], v[10:11] op_sel:[1,0,0] op_sel_hi:[1,1,1]
	v_pk_fma_f32 v[14:15], v[188:189], v[156:157], v[14:15] op_sel:[1,0,0] op_sel_hi:[1,1,1]
	v_pk_fma_f32 v[12:13], v[188:189], v[158:159], v[12:13] op_sel:[1,0,0] op_sel_hi:[1,1,1]
	v_pk_fma_f32 v[8:9], v[188:189], v[160:161], v[8:9] op_sel:[1,0,0] op_sel_hi:[1,1,1]
	ds_read_b128 v[154:157], v21 offset:1568
	ds_read_b128 v[158:161], v21 offset:1584
	s_waitcnt vmcnt(17) lgkmcnt(6)
	v_pk_fma_f32 v[10:11], v[190:191], v[162:163], v[10:11] op_sel_hi:[0,1,1]
	v_pk_fma_f32 v[14:15], v[190:191], v[164:165], v[14:15] op_sel_hi:[0,1,1]
	v_pk_fma_f32 v[12:13], v[190:191], v[166:167], v[12:13] op_sel_hi:[0,1,1]
	v_pk_fma_f32 v[8:9], v[190:191], v[168:169], v[8:9] op_sel_hi:[0,1,1]
	ds_read_b128 v[162:165], v21 offset:1600
	ds_read_b128 v[166:169], v21 offset:1616
	s_waitcnt vmcnt(16) lgkmcnt(6)
	v_pk_fma_f32 v[10:11], v[190:191], v[26:27], v[10:11] op_sel:[1,0,0] op_sel_hi:[1,1,1]
	v_pk_fma_f32 v[14:15], v[190:191], v[28:29], v[14:15] op_sel:[1,0,0] op_sel_hi:[1,1,1]
	v_pk_fma_f32 v[12:13], v[190:191], v[30:31], v[12:13] op_sel:[1,0,0] op_sel_hi:[1,1,1]
	v_pk_fma_f32 v[8:9], v[190:191], v[32:33], v[8:9] op_sel:[1,0,0] op_sel_hi:[1,1,1]
	ds_read_b128 v[26:29], v21 offset:1632
	ds_read_b128 v[30:33], v21 offset:1648
	s_waitcnt vmcnt(15) lgkmcnt(6)
	v_pk_fma_f32 v[10:11], v[192:193], v[146:147], v[10:11] op_sel_hi:[0,1,1]
	v_pk_fma_f32 v[14:15], v[192:193], v[148:149], v[14:15] op_sel_hi:[0,1,1]
	v_pk_fma_f32 v[12:13], v[192:193], v[150:151], v[12:13] op_sel_hi:[0,1,1]
	v_pk_fma_f32 v[8:9], v[192:193], v[152:153], v[8:9] op_sel_hi:[0,1,1]
	ds_read_b128 v[146:149], v21 offset:1664
	ds_read_b128 v[150:153], v21 offset:1680
	s_waitcnt vmcnt(14) lgkmcnt(6)
	v_pk_fma_f32 v[10:11], v[192:193], v[154:155], v[10:11] op_sel:[1,0,0] op_sel_hi:[1,1,1]
	v_pk_fma_f32 v[14:15], v[192:193], v[156:157], v[14:15] op_sel:[1,0,0] op_sel_hi:[1,1,1]
	v_pk_fma_f32 v[12:13], v[192:193], v[158:159], v[12:13] op_sel:[1,0,0] op_sel_hi:[1,1,1]
	v_pk_fma_f32 v[8:9], v[192:193], v[160:161], v[8:9] op_sel:[1,0,0] op_sel_hi:[1,1,1]
	ds_read_b128 v[154:157], v21 offset:1696
	ds_read_b128 v[158:161], v21 offset:1712
	s_waitcnt vmcnt(13) lgkmcnt(6)
	v_pk_fma_f32 v[10:11], v[194:195], v[162:163], v[10:11] op_sel_hi:[0,1,1]
	v_pk_fma_f32 v[14:15], v[194:195], v[164:165], v[14:15] op_sel_hi:[0,1,1]
	v_pk_fma_f32 v[12:13], v[194:195], v[166:167], v[12:13] op_sel_hi:[0,1,1]
	v_pk_fma_f32 v[8:9], v[194:195], v[168:169], v[8:9] op_sel_hi:[0,1,1]
	ds_read_b128 v[162:165], v21 offset:1728
	ds_read_b128 v[166:169], v21 offset:1744
	s_waitcnt vmcnt(12) lgkmcnt(6)
	v_pk_fma_f32 v[10:11], v[194:195], v[26:27], v[10:11] op_sel:[1,0,0] op_sel_hi:[1,1,1]
	v_pk_fma_f32 v[14:15], v[194:195], v[28:29], v[14:15] op_sel:[1,0,0] op_sel_hi:[1,1,1]
	v_pk_fma_f32 v[12:13], v[194:195], v[30:31], v[12:13] op_sel:[1,0,0] op_sel_hi:[1,1,1]
	v_pk_fma_f32 v[8:9], v[194:195], v[32:33], v[8:9] op_sel:[1,0,0] op_sel_hi:[1,1,1]
	ds_read_b128 v[26:29], v21 offset:1760
	ds_read_b128 v[30:33], v21 offset:1776
	s_waitcnt vmcnt(11) lgkmcnt(6)
	v_pk_fma_f32 v[10:11], v[196:197], v[146:147], v[10:11] op_sel_hi:[0,1,1]
	v_pk_fma_f32 v[14:15], v[196:197], v[148:149], v[14:15] op_sel_hi:[0,1,1]
	v_pk_fma_f32 v[12:13], v[196:197], v[150:151], v[12:13] op_sel_hi:[0,1,1]
	v_pk_fma_f32 v[8:9], v[196:197], v[152:153], v[8:9] op_sel_hi:[0,1,1]
	ds_read_b128 v[146:149], v21 offset:1792
	ds_read_b128 v[150:153], v21 offset:1808
	s_waitcnt vmcnt(10) lgkmcnt(6)
	v_pk_fma_f32 v[10:11], v[196:197], v[154:155], v[10:11] op_sel:[1,0,0] op_sel_hi:[1,1,1]
	v_pk_fma_f32 v[14:15], v[196:197], v[156:157], v[14:15] op_sel:[1,0,0] op_sel_hi:[1,1,1]
	v_pk_fma_f32 v[12:13], v[196:197], v[158:159], v[12:13] op_sel:[1,0,0] op_sel_hi:[1,1,1]
	v_pk_fma_f32 v[8:9], v[196:197], v[160:161], v[8:9] op_sel:[1,0,0] op_sel_hi:[1,1,1]
	ds_read_b128 v[154:157], v21 offset:1824
	ds_read_b128 v[158:161], v21 offset:1840
	s_waitcnt vmcnt(9) lgkmcnt(6)
	v_pk_fma_f32 v[10:11], v[198:199], v[162:163], v[10:11] op_sel_hi:[0,1,1]
	v_pk_fma_f32 v[14:15], v[198:199], v[164:165], v[14:15] op_sel_hi:[0,1,1]
	v_pk_fma_f32 v[12:13], v[198:199], v[166:167], v[12:13] op_sel_hi:[0,1,1]
	v_pk_fma_f32 v[8:9], v[198:199], v[168:169], v[8:9] op_sel_hi:[0,1,1]
	ds_read_b128 v[162:165], v21 offset:1856
	ds_read_b128 v[166:169], v21 offset:1872
	s_waitcnt vmcnt(8) lgkmcnt(6)
	v_pk_fma_f32 v[10:11], v[198:199], v[26:27], v[10:11] op_sel:[1,0,0] op_sel_hi:[1,1,1]
	v_pk_fma_f32 v[14:15], v[198:199], v[28:29], v[14:15] op_sel:[1,0,0] op_sel_hi:[1,1,1]
	v_pk_fma_f32 v[12:13], v[198:199], v[30:31], v[12:13] op_sel:[1,0,0] op_sel_hi:[1,1,1]
	v_pk_fma_f32 v[8:9], v[198:199], v[32:33], v[8:9] op_sel:[1,0,0] op_sel_hi:[1,1,1]
	ds_read_b128 v[26:29], v21 offset:1888
	ds_read_b128 v[30:33], v21 offset:1904
	s_waitcnt vmcnt(7) lgkmcnt(6)
	v_pk_fma_f32 v[10:11], v[200:201], v[146:147], v[10:11] op_sel_hi:[0,1,1]
	v_pk_fma_f32 v[14:15], v[200:201], v[148:149], v[14:15] op_sel_hi:[0,1,1]
	v_pk_fma_f32 v[12:13], v[200:201], v[150:151], v[12:13] op_sel_hi:[0,1,1]
	v_pk_fma_f32 v[8:9], v[200:201], v[152:153], v[8:9] op_sel_hi:[0,1,1]
	ds_read_b128 v[146:149], v21 offset:1920
	ds_read_b128 v[150:153], v21 offset:1936
	s_waitcnt vmcnt(6) lgkmcnt(6)
	v_pk_fma_f32 v[10:11], v[200:201], v[154:155], v[10:11] op_sel:[1,0,0] op_sel_hi:[1,1,1]
	v_pk_fma_f32 v[14:15], v[200:201], v[156:157], v[14:15] op_sel:[1,0,0] op_sel_hi:[1,1,1]
	v_pk_fma_f32 v[12:13], v[200:201], v[158:159], v[12:13] op_sel:[1,0,0] op_sel_hi:[1,1,1]
	v_pk_fma_f32 v[8:9], v[200:201], v[160:161], v[8:9] op_sel:[1,0,0] op_sel_hi:[1,1,1]
	ds_read_b128 v[154:157], v21 offset:1952
	ds_read_b128 v[158:161], v21 offset:1968
	s_waitcnt vmcnt(5) lgkmcnt(6)
	v_pk_fma_f32 v[10:11], v[202:203], v[162:163], v[10:11] op_sel_hi:[0,1,1]
	v_pk_fma_f32 v[14:15], v[202:203], v[164:165], v[14:15] op_sel_hi:[0,1,1]
	v_pk_fma_f32 v[12:13], v[202:203], v[166:167], v[12:13] op_sel_hi:[0,1,1]
	v_pk_fma_f32 v[8:9], v[202:203], v[168:169], v[8:9] op_sel_hi:[0,1,1]
	ds_read_b128 v[162:165], v21 offset:1984
	ds_read_b128 v[166:169], v21 offset:2000
	s_waitcnt vmcnt(4) lgkmcnt(6)
	v_pk_fma_f32 v[10:11], v[202:203], v[26:27], v[10:11] op_sel:[1,0,0] op_sel_hi:[1,1,1]
	v_pk_fma_f32 v[14:15], v[202:203], v[28:29], v[14:15] op_sel:[1,0,0] op_sel_hi:[1,1,1]
	v_pk_fma_f32 v[12:13], v[202:203], v[30:31], v[12:13] op_sel:[1,0,0] op_sel_hi:[1,1,1]
	v_pk_fma_f32 v[8:9], v[202:203], v[32:33], v[8:9] op_sel:[1,0,0] op_sel_hi:[1,1,1]
	ds_read_b128 v[26:29], v21 offset:2016
	ds_read_b128 v[30:33], v21 offset:2032
	s_waitcnt vmcnt(3) lgkmcnt(6)
	v_pk_fma_f32 v[10:11], v[22:23], v[146:147], v[10:11] op_sel_hi:[0,1,1]
	v_pk_fma_f32 v[14:15], v[22:23], v[148:149], v[14:15] op_sel_hi:[0,1,1]
	v_pk_fma_f32 v[12:13], v[22:23], v[150:151], v[12:13] op_sel_hi:[0,1,1]
	v_pk_fma_f32 v[8:9], v[22:23], v[152:153], v[8:9] op_sel_hi:[0,1,1]
	s_waitcnt vmcnt(2) lgkmcnt(4)
	v_pk_fma_f32 v[10:11], v[22:23], v[154:155], v[10:11] op_sel:[1,0,0] op_sel_hi:[1,1,1]
	v_pk_fma_f32 v[14:15], v[22:23], v[156:157], v[14:15] op_sel:[1,0,0] op_sel_hi:[1,1,1]
	v_pk_fma_f32 v[12:13], v[22:23], v[158:159], v[12:13] op_sel:[1,0,0] op_sel_hi:[1,1,1]
	v_pk_fma_f32 v[8:9], v[22:23], v[160:161], v[8:9] op_sel:[1,0,0] op_sel_hi:[1,1,1]
	s_waitcnt vmcnt(1) lgkmcnt(2)
	v_pk_fma_f32 v[10:11], v[24:25], v[162:163], v[10:11] op_sel_hi:[0,1,1]
	v_pk_fma_f32 v[14:15], v[24:25], v[164:165], v[14:15] op_sel_hi:[0,1,1]
	v_pk_fma_f32 v[12:13], v[24:25], v[166:167], v[12:13] op_sel_hi:[0,1,1]
	v_pk_fma_f32 v[8:9], v[24:25], v[168:169], v[8:9] op_sel_hi:[0,1,1]
	s_waitcnt vmcnt(0) lgkmcnt(0)
	v_pk_fma_f32 v[10:11], v[24:25], v[26:27], v[10:11] op_sel:[1,0,0] op_sel_hi:[1,1,1]
	v_pk_fma_f32 v[14:15], v[24:25], v[28:29], v[14:15] op_sel:[1,0,0] op_sel_hi:[1,1,1]
	v_pk_fma_f32 v[12:13], v[24:25], v[30:31], v[12:13] op_sel:[1,0,0] op_sel_hi:[1,1,1]
	v_pk_fma_f32 v[8:9], v[24:25], v[32:33], v[8:9] op_sel:[1,0,0] op_sel_hi:[1,1,1]
	s_cmpk_eq_i32 s22, 0x1000
	s_cbranch_scc0 .LBB0_22
	v_add_u32_e32 v6, s43, v17
	ds_write2st64_b32 v6, v10, v11 offset0:128 offset1:129
	ds_write2st64_b32 v6, v14, v15 offset0:130 offset1:131
	ds_write2st64_b32 v6, v12, v13 offset0:132 offset1:133
	ds_write2st64_b32 v6, v8, v9 offset0:134 offset1:135
	v_add_u32_e32 v6, s14, v66
	v_ashrrev_i32_e32 v7, 31, v6
	v_lshl_add_u64 v[6:7], v[6:7], 2, s[16:17]
	s_waitcnt lgkmcnt(0)
	s_barrier
	global_load_dword v16, v[6:7], off
	ds_read2st64_b32 v[8:9], v20 offset0:128 offset1:136
	ds_read2st64_b32 v[10:11], v20 offset0:144 offset1:152
	ds_read2st64_b32 v[12:13], v20 offset0:160 offset1:168
	ds_read2st64_b32 v[14:15], v20 offset0:176 offset1:184
	v_lshl_add_u64 v[6:7], v[4:5], 0, s[18:19]
	s_add_i32 s45, s45, s76
	v_lshl_add_u64 v[6:7], s[14:15], 2, v[6:7]
	s_cmpk_gt_i32 s45, 0x19f
	v_lshl_add_u64 v[6:7], v[6:7], 0, v[2:3]
	s_waitcnt vmcnt(0) lgkmcnt(3)
	v_add_f32_e32 v8, v16, v8
	v_add_f32_e32 v8, v8, v9
	s_waitcnt lgkmcnt(2)
	v_add_f32_e32 v8, v8, v10
	v_add_f32_e32 v8, v8, v11
	s_waitcnt lgkmcnt(1)
	v_add_f32_e32 v8, v8, v12
	v_add_f32_e32 v8, v8, v13
	s_waitcnt lgkmcnt(0)
	v_add_f32_e32 v8, v8, v14
	v_add_f32_e32 v8, v8, v15
	global_store_dword v[6:7], v8, off sc1
	s_barrier
	s_cbranch_scc0 .LBB0_16
